# hg<true> state prefix over earlier segments pipelined two deep (second register set, <=63 loads in flight) (run 1)
# speedup vs baseline: 1.0026x; 1.0026x over previous
; #define lane lane_id()
; template <bool FULL, bool STORE = true>
; __device__ __forceinline__ void hg_item(const Prm& P, LAS unsigned char* lds, int item, int wave) {
;     ...
;     f32x16 S[2];
; #pragma unroll
;     for (int i = 0; i < 2; ++i)
; #pragma unroll
;         for (int r = 0; r < 16; ++r) S[i][r] = 0.f;
;     float sumlog0 = 0.f, sumlog1 = 0.f;
;     if (FULL) {
;         for (int s2 = 0; s2 < seg; ++s2) { const int it2 = item - seg + s2;
; #pragma unroll
;             for (int g4 = 0; g4 < 4; ++g4) { const f32x4 d = *(const f32x4*)(DEC + it2 * 128 + kb * 32 + 8 * g4 + 4 * lh);
; #pragma unroll
;                 for (int i = 0; i < 2; ++i)
; #pragma unroll
;                     for (int j = 0; j < 4; ++j) { const int r = 4 * g4 + j; S[i][r] = d[j] * S[i][r] + AGG[(size_t)((it2 * 8 + wave) * 2 + i) * 1024 + r * 64 + lane]; } } }
.LBB0_822:
	v_mbcnt_lo_u32_b32 v32, -1, 0
	v_mbcnt_hi_u32_b32 v32, -1, v32
	s_and_b32 s26, s91, 7
	v_ashrrev_i32_e32 v40, 5, v32
	s_cmp_eq_u32 s26, 0
	v_lshlrev_b32_e32 v34, 2, v40
	v_mov_b32_e32 v31, 0
	v_mov_b32_e32 v30, 0
	v_mov_b32_e32 v29, 0
	v_mov_b32_e32 v28, 0
	v_mov_b32_e32 v27, 0
	v_mov_b32_e32 v26, 0
	v_mov_b32_e32 v25, 0
	v_mov_b32_e32 v24, 0
	v_mov_b32_e32 v23, 0
	v_mov_b32_e32 v22, 0
	v_mov_b32_e32 v21, 0
	v_mov_b32_e32 v20, 0
	v_mov_b32_e32 v19, 0
	v_mov_b32_e32 v18, 0
	v_mov_b32_e32 v17, 0
	v_mov_b32_e32 v16, 0
	v_mov_b32_e32 v15, 0
	v_mov_b32_e32 v14, 0
	v_mov_b32_e32 v13, 0
	v_mov_b32_e32 v12, 0
	v_mov_b32_e32 v11, 0
	v_mov_b32_e32 v10, 0
	v_mov_b32_e32 v9, 0
	v_mov_b32_e32 v8, 0
	v_mov_b32_e32 v7, 0
	v_mov_b32_e32 v6, 0
	v_mov_b32_e32 v5, 0
	v_mov_b32_e32 v4, 0
	v_mov_b32_e32 v3, 0
	v_mov_b32_e32 v2, 0
	v_mov_b32_e32 v1, 0
	v_mov_b32_e32 v0, 0
	s_cbranch_scc1 .LBB0_825
	s_lshr_b32 s19, s91, 3
	s_lshl_b32 s22, s19, 10
	s_lshl_b32 s18, s19, 7
	v_readlane_b32 s21, v255, 26
	s_ashr_i32 s23, s22, 31
	s_and_b32 s20, s2, 7
	s_add_i32 s18, s21, s18
	s_lshl_b64 s[22:23], s[22:23], 2
	v_readlane_b32 s19, v255, 52
	v_readlane_b32 s24, v255, 27
	s_add_u32 s22, s19, s22
	v_readlane_b32 s19, v255, 53
	v_ashrrev_i32_e32 v35, 31, v34
	v_ashrrev_i32_e32 v33, 31, v32
	v_readlane_b32 s25, v255, 28
	s_addc_u32 s23, s19, s23
	v_mov_b32_e32 v0, 0
	v_lshl_add_u64 v[36:37], v[32:33], 2, s[24:25]
	v_lshl_add_u64 v[38:39], v[34:35], 2, s[22:23]
	v_mov_b32_e32 v1, v0
	v_mov_b32_e32 v2, v0
	v_mov_b32_e32 v3, v0
	v_mov_b32_e32 v4, v0
	v_mov_b32_e32 v5, v0
	v_mov_b32_e32 v6, v0
	v_mov_b32_e32 v7, v0
	v_mov_b32_e32 v8, v0
	v_mov_b32_e32 v9, v0
	v_mov_b32_e32 v10, v0
	v_mov_b32_e32 v11, v0
	v_mov_b32_e32 v12, v0
	v_mov_b32_e32 v13, v0
	v_mov_b32_e32 v14, v0
	v_mov_b32_e32 v15, v0
	v_mov_b32_e32 v16, v0
	v_mov_b32_e32 v17, v0
	v_mov_b32_e32 v18, v0
	v_mov_b32_e32 v19, v0
	v_mov_b32_e32 v20, v0
	v_mov_b32_e32 v21, v0
	v_mov_b32_e32 v22, v0
	v_mov_b32_e32 v23, v0
	v_mov_b32_e32 v24, v0
	v_mov_b32_e32 v25, v0
	v_mov_b32_e32 v26, v0
	v_mov_b32_e32 v27, v0
	v_mov_b32_e32 v28, v0
	v_mov_b32_e32 v29, v0
	v_mov_b32_e32 v30, v0
	v_mov_b32_e32 v31, v0
	s_ashr_i32 s19, s18, 31
	s_add_i32 s22, s18, 1
	s_lshl_b64 s[24:25], s[18:19], 12
	s_ashr_i32 s23, s22, 31
	v_lshl_add_u64 v[100:101], v[36:37], 0, s[24:25]
	s_lshl_b64 s[22:23], s[22:23], 12
	v_lshl_add_u64 v[102:103], v[36:37], 0, s[22:23]
	global_load_dwordx4 v[42:45], v[38:39], off offset:-64
	global_load_dwordx4 v[46:49], v[38:39], off offset:-32
	global_load_dwordx4 v[50:53], v[38:39], off
	global_load_dwordx4 v[54:57], v[38:39], off offset:32
	global_load_dword v62, v[100:101], off
	global_load_dword v63, v[100:101], off offset:256
	global_load_dword v64, v[100:101], off offset:512
	global_load_dword v65, v[100:101], off offset:768
	global_load_dword v66, v[100:101], off offset:1024
	global_load_dword v67, v[100:101], off offset:1280
	global_load_dword v68, v[100:101], off offset:1536
	global_load_dword v69, v[100:101], off offset:1792
	global_load_dword v70, v[100:101], off offset:2048
	global_load_dword v71, v[100:101], off offset:2304
	global_load_dword v72, v[100:101], off offset:2560
	global_load_dword v73, v[100:101], off offset:2816
	global_load_dword v76, v[100:101], off offset:3072
	global_load_dword v77, v[100:101], off offset:3328
	global_load_dword v78, v[100:101], off offset:3584
	global_load_dword v79, v[100:101], off offset:3840
	global_load_dword v58, v[102:103], off
	global_load_dword v59, v[102:103], off offset:256
	global_load_dword v80, v[102:103], off offset:512
	global_load_dword v81, v[102:103], off offset:768
	global_load_dword v82, v[102:103], off offset:1024
	global_load_dword v83, v[102:103], off offset:1280
	global_load_dword v84, v[102:103], off offset:1536
	global_load_dword v85, v[102:103], off offset:1792
	global_load_dword v86, v[102:103], off offset:2048
	global_load_dword v87, v[102:103], off offset:2304
	global_load_dword v88, v[102:103], off offset:2560
	global_load_dword v89, v[102:103], off offset:2816
	global_load_dword v90, v[102:103], off offset:3072
	global_load_dword v91, v[102:103], off offset:3328
	global_load_dword v92, v[102:103], off offset:3584
	global_load_dword v93, v[102:103], off offset:3840
	s_mov_b64 s[22:23], 0x200
	v_lshl_add_u64 v[38:39], v[38:39], 0, s[22:23]
	s_add_i32 s18, s18, 16
	s_add_i32 s20, s20, -1
; #define lane lane_id()
; template <bool FULL, bool STORE = true>
; __device__ __forceinline__ void hg_item(const Prm& P, LAS unsigned char* lds, int item, int wave) {
;     ...
;         for (int s2 = 0; s2 < seg; ++s2) { const int it2 = item - seg + s2;
; #pragma unroll
;             for (int g4 = 0; g4 < 4; ++g4) { const f32x4 d = *(const f32x4*)(DEC + it2 * 128 + kb * 32 + 8 * g4 + 4 * lh);
; #pragma unroll
;                 for (int i = 0; i < 2; ++i)
; #pragma unroll
;                     for (int j = 0; j < 4; ++j) { const int r = 4 * g4 + j; S[i][r] = d[j] * S[i][r] + AGG[(size_t)((it2 * 8 + wave) * 2 + i) * 1024 + r * 64 + lane]; } } }
.Lmy_pf_top:
	s_cmp_eq_u32 s20, 0
	s_cbranch_scc1 .Lmy_pf_drainA
	s_ashr_i32 s19, s18, 31
	s_add_i32 s22, s18, 1
	s_lshl_b64 s[24:25], s[18:19], 12
	s_ashr_i32 s23, s22, 31
	v_lshl_add_u64 v[100:101], v[36:37], 0, s[24:25]
	s_lshl_b64 s[22:23], s[22:23], 12
	v_lshl_add_u64 v[102:103], v[36:37], 0, s[22:23]
	global_load_dwordx4 v[172:175], v[38:39], off offset:-64
	global_load_dwordx4 v[176:179], v[38:39], off offset:-32
	global_load_dwordx4 v[180:183], v[38:39], off
	global_load_dwordx4 v[184:187], v[38:39], off offset:32
	global_load_dword v188, v[100:101], off
	global_load_dword v189, v[100:101], off offset:256
	global_load_dword v190, v[100:101], off offset:512
	global_load_dword v191, v[100:101], off offset:768
	global_load_dword v192, v[100:101], off offset:1024
	global_load_dword v193, v[100:101], off offset:1280
	global_load_dword v194, v[100:101], off offset:1536
	global_load_dword v195, v[100:101], off offset:1792
	global_load_dword v196, v[100:101], off offset:2048
	global_load_dword v197, v[100:101], off offset:2304
	global_load_dword v198, v[100:101], off offset:2560
	global_load_dword v199, v[100:101], off offset:2816
	global_load_dword v200, v[100:101], off offset:3072
	global_load_dword v201, v[100:101], off offset:3328
	global_load_dword v202, v[100:101], off offset:3584
	global_load_dword v203, v[100:101], off offset:3840
	global_load_dword v204, v[102:103], off
	global_load_dword v205, v[102:103], off offset:256
	global_load_dword v206, v[102:103], off offset:512
	global_load_dword v207, v[102:103], off offset:768
	global_load_dword v208, v[102:103], off offset:1024
	global_load_dword v209, v[102:103], off offset:1280
	global_load_dword v210, v[102:103], off offset:1536
	s_mov_b64 s[22:23], 0x200
	v_lshl_add_u64 v[38:39], v[38:39], 0, s[22:23]
	s_add_i32 s18, s18, 16
	s_add_i32 s20, s20, -1
	s_waitcnt vmcnt(57)
	v_pk_fma_f32 v[0:1], v[0:1], v[42:43], v[62:63]
	global_load_dword v211, v[102:103], off offset:1792
	s_waitcnt vmcnt(56)
	v_pk_fma_f32 v[2:3], v[2:3], v[44:45], v[64:65]
	global_load_dword v212, v[102:103], off offset:2048
	s_waitcnt vmcnt(55)
	v_pk_fma_f32 v[4:5], v[4:5], v[46:47], v[66:67]
	global_load_dword v213, v[102:103], off offset:2304
	s_waitcnt vmcnt(54)
	v_pk_fma_f32 v[6:7], v[6:7], v[48:49], v[68:69]
	global_load_dword v214, v[102:103], off offset:2560
	s_waitcnt vmcnt(53)
	v_pk_fma_f32 v[8:9], v[8:9], v[50:51], v[70:71]
	global_load_dword v215, v[102:103], off offset:2816
	s_waitcnt vmcnt(52)
	v_pk_fma_f32 v[10:11], v[10:11], v[52:53], v[72:73]
	global_load_dword v216, v[102:103], off offset:3072
	s_waitcnt vmcnt(51)
	v_pk_fma_f32 v[12:13], v[12:13], v[54:55], v[76:77]
	global_load_dword v217, v[102:103], off offset:3328
	s_waitcnt vmcnt(50)
	v_pk_fma_f32 v[14:15], v[14:15], v[56:57], v[78:79]
	global_load_dword v218, v[102:103], off offset:3584
	s_waitcnt vmcnt(49)
	v_pk_fma_f32 v[16:17], v[16:17], v[42:43], v[58:59]
	global_load_dword v219, v[102:103], off offset:3840
	s_waitcnt vmcnt(48)
	v_pk_fma_f32 v[18:19], v[18:19], v[44:45], v[80:81]
	s_waitcnt vmcnt(46)
	v_pk_fma_f32 v[20:21], v[20:21], v[46:47], v[82:83]
	s_waitcnt vmcnt(44)
	v_pk_fma_f32 v[22:23], v[22:23], v[48:49], v[84:85]
	s_waitcnt vmcnt(42)
	v_pk_fma_f32 v[24:25], v[24:25], v[50:51], v[86:87]
	s_waitcnt vmcnt(40)
	v_pk_fma_f32 v[26:27], v[26:27], v[52:53], v[88:89]
	s_waitcnt vmcnt(38)
	v_pk_fma_f32 v[28:29], v[28:29], v[54:55], v[90:91]
	s_waitcnt vmcnt(36)
	v_pk_fma_f32 v[30:31], v[30:31], v[56:57], v[92:93]
	s_cmp_eq_u32 s20, 0
	s_cbranch_scc1 .Lmy_pf_drainB
	s_ashr_i32 s19, s18, 31
	s_add_i32 s22, s18, 1
	s_lshl_b64 s[24:25], s[18:19], 12
	s_ashr_i32 s23, s22, 31
	v_lshl_add_u64 v[100:101], v[36:37], 0, s[24:25]
	s_lshl_b64 s[22:23], s[22:23], 12
	v_lshl_add_u64 v[102:103], v[36:37], 0, s[22:23]
	global_load_dwordx4 v[42:45], v[38:39], off offset:-64
	global_load_dwordx4 v[46:49], v[38:39], off offset:-32
	global_load_dwordx4 v[50:53], v[38:39], off
	global_load_dwordx4 v[54:57], v[38:39], off offset:32
	global_load_dword v62, v[100:101], off
	global_load_dword v63, v[100:101], off offset:256
	global_load_dword v64, v[100:101], off offset:512
	global_load_dword v65, v[100:101], off offset:768
	global_load_dword v66, v[100:101], off offset:1024
	global_load_dword v67, v[100:101], off offset:1280
	global_load_dword v68, v[100:101], off offset:1536
	global_load_dword v69, v[100:101], off offset:1792
	global_load_dword v70, v[100:101], off offset:2048
	global_load_dword v71, v[100:101], off offset:2304
	global_load_dword v72, v[100:101], off offset:2560
	global_load_dword v73, v[100:101], off offset:2816
	global_load_dword v76, v[100:101], off offset:3072
	global_load_dword v77, v[100:101], off offset:3328
	global_load_dword v78, v[100:101], off offset:3584
	global_load_dword v79, v[100:101], off offset:3840
	global_load_dword v58, v[102:103], off
	global_load_dword v59, v[102:103], off offset:256
	global_load_dword v80, v[102:103], off offset:512
	global_load_dword v81, v[102:103], off offset:768
	global_load_dword v82, v[102:103], off offset:1024
	global_load_dword v83, v[102:103], off offset:1280
	global_load_dword v84, v[102:103], off offset:1536
	s_mov_b64 s[22:23], 0x200
	v_lshl_add_u64 v[38:39], v[38:39], 0, s[22:23]
	s_add_i32 s18, s18, 16
	s_add_i32 s20, s20, -1
	s_waitcnt vmcnt(57)
	v_pk_fma_f32 v[0:1], v[0:1], v[172:173], v[188:189]
	global_load_dword v85, v[102:103], off offset:1792
	s_waitcnt vmcnt(56)
	v_pk_fma_f32 v[2:3], v[2:3], v[174:175], v[190:191]
	global_load_dword v86, v[102:103], off offset:2048
	s_waitcnt vmcnt(55)
	v_pk_fma_f32 v[4:5], v[4:5], v[176:177], v[192:193]
	global_load_dword v87, v[102:103], off offset:2304
	s_waitcnt vmcnt(54)
	v_pk_fma_f32 v[6:7], v[6:7], v[178:179], v[194:195]
	global_load_dword v88, v[102:103], off offset:2560
	s_waitcnt vmcnt(53)
	v_pk_fma_f32 v[8:9], v[8:9], v[180:181], v[196:197]
	global_load_dword v89, v[102:103], off offset:2816
	s_waitcnt vmcnt(52)
	v_pk_fma_f32 v[10:11], v[10:11], v[182:183], v[198:199]
	global_load_dword v90, v[102:103], off offset:3072
	s_waitcnt vmcnt(51)
	v_pk_fma_f32 v[12:13], v[12:13], v[184:185], v[200:201]
	global_load_dword v91, v[102:103], off offset:3328
	s_waitcnt vmcnt(50)
	v_pk_fma_f32 v[14:15], v[14:15], v[186:187], v[202:203]
	global_load_dword v92, v[102:103], off offset:3584
	s_waitcnt vmcnt(49)
	v_pk_fma_f32 v[16:17], v[16:17], v[172:173], v[204:205]
	global_load_dword v93, v[102:103], off offset:3840
	s_waitcnt vmcnt(48)
	v_pk_fma_f32 v[18:19], v[18:19], v[174:175], v[206:207]
	s_waitcnt vmcnt(46)
	v_pk_fma_f32 v[20:21], v[20:21], v[176:177], v[208:209]
	s_waitcnt vmcnt(44)
	v_pk_fma_f32 v[22:23], v[22:23], v[178:179], v[210:211]
	s_waitcnt vmcnt(42)
	v_pk_fma_f32 v[24:25], v[24:25], v[180:181], v[212:213]
	s_waitcnt vmcnt(40)
	v_pk_fma_f32 v[26:27], v[26:27], v[182:183], v[214:215]
	s_waitcnt vmcnt(38)
	v_pk_fma_f32 v[28:29], v[28:29], v[184:185], v[216:217]
	s_waitcnt vmcnt(36)
	v_pk_fma_f32 v[30:31], v[30:31], v[186:187], v[218:219]
	s_branch .Lmy_pf_top
; #define lane lane_id()
; template <bool FULL, bool STORE = true>
; __device__ __forceinline__ void hg_item(const Prm& P, LAS unsigned char* lds, int item, int wave) {
;     ...
;         for (int s2 = 0; s2 < seg; ++s2) { const int it2 = item - seg + s2;
; #pragma unroll
;             for (int g4 = 0; g4 < 4; ++g4) { const f32x4 d = *(const f32x4*)(DEC + it2 * 128 + kb * 32 + 8 * g4 + 4 * lh);
; #pragma unroll
;                 for (int i = 0; i < 2; ++i)
; #pragma unroll
;                     for (int j = 0; j < 4; ++j) { const int r = 4 * g4 + j; S[i][r] = d[j] * S[i][r] + AGG[(size_t)((it2 * 8 + wave) * 2 + i) * 1024 + r * 64 + lane]; } } }
.Lmy_pf_drainA:
	s_waitcnt vmcnt(30)
	v_pk_fma_f32 v[0:1], v[0:1], v[42:43], v[62:63]
	s_waitcnt vmcnt(28)
	v_pk_fma_f32 v[2:3], v[2:3], v[44:45], v[64:65]
	s_waitcnt vmcnt(26)
	v_pk_fma_f32 v[4:5], v[4:5], v[46:47], v[66:67]
	s_waitcnt vmcnt(24)
	v_pk_fma_f32 v[6:7], v[6:7], v[48:49], v[68:69]
	s_waitcnt vmcnt(22)
	v_pk_fma_f32 v[8:9], v[8:9], v[50:51], v[70:71]
	s_waitcnt vmcnt(20)
	v_pk_fma_f32 v[10:11], v[10:11], v[52:53], v[72:73]
	s_waitcnt vmcnt(18)
	v_pk_fma_f32 v[12:13], v[12:13], v[54:55], v[76:77]
	s_waitcnt vmcnt(16)
	v_pk_fma_f32 v[14:15], v[14:15], v[56:57], v[78:79]
	s_waitcnt vmcnt(14)
	v_pk_fma_f32 v[16:17], v[16:17], v[42:43], v[58:59]
	s_waitcnt vmcnt(12)
	v_pk_fma_f32 v[18:19], v[18:19], v[44:45], v[80:81]
	s_waitcnt vmcnt(10)
	v_pk_fma_f32 v[20:21], v[20:21], v[46:47], v[82:83]
	s_waitcnt vmcnt(8)
	v_pk_fma_f32 v[22:23], v[22:23], v[48:49], v[84:85]
	s_waitcnt vmcnt(6)
	v_pk_fma_f32 v[24:25], v[24:25], v[50:51], v[86:87]
	s_waitcnt vmcnt(4)
	v_pk_fma_f32 v[26:27], v[26:27], v[52:53], v[88:89]
	s_waitcnt vmcnt(2)
	v_pk_fma_f32 v[28:29], v[28:29], v[54:55], v[90:91]
	s_waitcnt vmcnt(0)
	v_pk_fma_f32 v[30:31], v[30:31], v[56:57], v[92:93]
	s_branch .LBB0_825
.Lmy_pf_drainB:
	s_waitcnt vmcnt(30)
	v_pk_fma_f32 v[0:1], v[0:1], v[172:173], v[188:189]
	s_waitcnt vmcnt(28)
	v_pk_fma_f32 v[2:3], v[2:3], v[174:175], v[190:191]
	s_waitcnt vmcnt(26)
	v_pk_fma_f32 v[4:5], v[4:5], v[176:177], v[192:193]
	s_waitcnt vmcnt(24)
	v_pk_fma_f32 v[6:7], v[6:7], v[178:179], v[194:195]
	s_waitcnt vmcnt(22)
	v_pk_fma_f32 v[8:9], v[8:9], v[180:181], v[196:197]
	s_waitcnt vmcnt(20)
	v_pk_fma_f32 v[10:11], v[10:11], v[182:183], v[198:199]
	s_waitcnt vmcnt(18)
	v_pk_fma_f32 v[12:13], v[12:13], v[184:185], v[200:201]
	s_waitcnt vmcnt(16)
	v_pk_fma_f32 v[14:15], v[14:15], v[186:187], v[202:203]
	s_waitcnt vmcnt(14)
	v_pk_fma_f32 v[16:17], v[16:17], v[172:173], v[204:205]
	s_waitcnt vmcnt(12)
	v_pk_fma_f32 v[18:19], v[18:19], v[174:175], v[206:207]
	s_waitcnt vmcnt(10)
	v_pk_fma_f32 v[20:21], v[20:21], v[176:177], v[208:209]
	s_waitcnt vmcnt(8)
	v_pk_fma_f32 v[22:23], v[22:23], v[178:179], v[210:211]
	s_waitcnt vmcnt(6)
	v_pk_fma_f32 v[24:25], v[24:25], v[180:181], v[212:213]
	s_waitcnt vmcnt(4)
	v_pk_fma_f32 v[26:27], v[26:27], v[182:183], v[214:215]
	s_waitcnt vmcnt(2)
	v_pk_fma_f32 v[28:29], v[28:29], v[184:185], v[216:217]
	s_waitcnt vmcnt(0)
	v_pk_fma_f32 v[30:31], v[30:31], v[186:187], v[218:219]
